# fuse branch and merge GEMM phases: grid barrier replaced by arrive counter + deferred wait before the first merge epilogue (sc1 PROJ stores), merge tile order reversed
# speedup vs baseline: 1.0217x; 1.0217x over previous
.LBB0_1538:
	v_lshl_add_u32 v150, s26, 8, v146
	v_lshl_or_b32 v144, s20, 8, v148
	v_ashrrev_i32_e32 v151, 31, v150
	v_ashrrev_i32_e32 v145, 31, v144
	v_lshlrev_b64 v[152:153], 13, v[150:151]
	v_lshl_add_u64 v[152:153], s[10:11], 0, v[152:153]
	v_lshlrev_b64 v[154:155], 1, v[144:145]
	v_lshl_add_u64 v[144:145], v[152:153], 0, v[154:155]
	v_cvt_pk_bf16_f32 v126, v126, v127
	v_cvt_pk_bf16_f32 v127, v128, v129
	v_cvt_pk_bf16_f32 v128, v122, v123
	v_cvt_pk_bf16_f32 v129, v124, v125
	global_store_dwordx4 v[144:145], v[126:129], off sc1
	v_cvt_pk_bf16_f32 v114, v114, v115
	v_cvt_pk_bf16_f32 v115, v116, v117
	v_cvt_pk_bf16_f32 v116, v106, v107
	v_or_b32_e32 v106, 16, v150
	v_ashrrev_i32_e32 v107, 31, v106
	v_lshlrev_b64 v[106:107], 13, v[106:107]
	v_lshl_add_u64 v[106:107], s[10:11], 0, v[106:107]
	v_cvt_pk_bf16_f32 v117, v108, v109
	global_store_dwordx4 v[144:145], v[114:117], off offset:256 sc1
	s_mov_b32 s6, 0x100000
	s_nop 0
	v_lshl_add_u64 v[114:115], v[106:107], 0, v[154:155]
	v_cvt_pk_bf16_f32 v106, v118, v119
	v_cvt_pk_bf16_f32 v107, v120, v121
	v_cvt_pk_bf16_f32 v108, v110, v111
	v_cvt_pk_bf16_f32 v109, v112, v113
	global_store_dwordx4 v[114:115], v[106:109], off sc1
	v_cvt_pk_bf16_f32 v98, v98, v99
	v_cvt_pk_bf16_f32 v99, v100, v101
	v_cvt_pk_bf16_f32 v100, v90, v91
	v_or_b32_e32 v90, 32, v150
	v_ashrrev_i32_e32 v91, 31, v90
	v_lshlrev_b64 v[90:91], 13, v[90:91]
	v_lshl_add_u64 v[90:91], s[10:11], 0, v[90:91]
	v_cvt_pk_bf16_f32 v101, v92, v93
	global_store_dwordx4 v[114:115], v[98:101], off offset:256 sc1
	s_nop 1
	v_lshl_add_u64 v[98:99], v[90:91], 0, v[154:155]
	v_cvt_pk_bf16_f32 v90, v102, v103
	v_cvt_pk_bf16_f32 v91, v104, v105
	v_cvt_pk_bf16_f32 v92, v94, v95
	v_cvt_pk_bf16_f32 v93, v96, v97
	global_store_dwordx4 v[98:99], v[90:93], off sc1
	v_cvt_pk_bf16_f32 v82, v82, v83
	v_cvt_pk_bf16_f32 v83, v84, v85
	v_cvt_pk_bf16_f32 v84, v74, v75
	v_or_b32_e32 v74, 48, v150
	v_ashrrev_i32_e32 v75, 31, v74
	v_lshlrev_b64 v[74:75], 13, v[74:75]
	v_lshl_add_u64 v[74:75], s[10:11], 0, v[74:75]
	v_cvt_pk_bf16_f32 v85, v76, v77
	global_store_dwordx4 v[98:99], v[82:85], off offset:256 sc1
	s_nop 1
	v_lshl_add_u64 v[82:83], v[74:75], 0, v[154:155]
	v_cvt_pk_bf16_f32 v74, v86, v87
	v_cvt_pk_bf16_f32 v75, v88, v89
	v_cvt_pk_bf16_f32 v76, v78, v79
	v_cvt_pk_bf16_f32 v77, v80, v81
	global_store_dwordx4 v[82:83], v[74:77], off sc1
	v_cvt_pk_bf16_f32 v70, v70, v71
	v_cvt_pk_bf16_f32 v71, v72, v73
	v_cvt_pk_bf16_f32 v72, v66, v67
	v_cvt_pk_bf16_f32 v73, v68, v69
	global_store_dwordx4 v[82:83], v[70:73], off offset:256 sc1
	v_cvt_pk_bf16_f32 v62, v62, v63
	v_cvt_pk_bf16_f32 v63, v64, v65
	v_cvt_pk_bf16_f32 v64, v58, v59
	v_add_co_u32_e32 v58, vcc, s6, v144
	v_lshl_add_u64 v[66:67], v[144:145], 0, s[50:51]
	s_nop 0
	v_addc_co_u32_e32 v59, vcc, 0, v145, vcc
	v_cvt_pk_bf16_f32 v65, v60, v61
	global_store_dwordx4 v[58:59], v[62:65], off sc1
	v_cvt_pk_bf16_f32 v50, v50, v51
	v_cvt_pk_bf16_f32 v51, v52, v53
	s_mov_b64 s[6:7], 0x120000
	v_cvt_pk_bf16_f32 v52, v42, v43
	v_cvt_pk_bf16_f32 v53, v44, v45
	global_store_dwordx4 v[66:67], v[50:53], off offset:256 sc1
	v_cvt_pk_bf16_f32 v42, v54, v55
	v_cvt_pk_bf16_f32 v43, v56, v57
	v_cvt_pk_bf16_f32 v44, v46, v47
	v_cvt_pk_bf16_f32 v45, v48, v49
	s_nop 1
	v_lshl_add_u64 v[50:51], v[144:145], 0, s[6:7]
	s_mov_b32 s6, 0x120000
	v_add_co_u32_e32 v46, vcc, s6, v144
	s_mov_b64 s[6:7], 0x140000
	s_nop 0
	v_addc_co_u32_e32 v47, vcc, 0, v145, vcc
	global_store_dwordx4 v[46:47], v[42:45], off sc1
	v_cvt_pk_bf16_f32 v34, v34, v35
	v_cvt_pk_bf16_f32 v35, v36, v37
	v_cvt_pk_bf16_f32 v36, v26, v27
	v_cvt_pk_bf16_f32 v37, v28, v29
	global_store_dwordx4 v[50:51], v[34:37], off offset:256 sc1
	v_cvt_pk_bf16_f32 v26, v38, v39
	v_cvt_pk_bf16_f32 v27, v40, v41
	v_cvt_pk_bf16_f32 v28, v30, v31
	v_cvt_pk_bf16_f32 v29, v32, v33
	s_nop 1
	v_lshl_add_u64 v[34:35], v[144:145], 0, s[6:7]
	s_mov_b32 s6, 0x140000
	v_add_co_u32_e32 v30, vcc, s6, v144
	s_mov_b64 s[6:7], 0x160000
	s_nop 0
	v_addc_co_u32_e32 v31, vcc, 0, v145, vcc
	global_store_dwordx4 v[30:31], v[26:29], off sc1
	v_cvt_pk_bf16_f32 v18, v18, v19
	v_cvt_pk_bf16_f32 v19, v20, v21
	v_cvt_pk_bf16_f32 v20, v10, v11
	v_cvt_pk_bf16_f32 v21, v12, v13
	global_store_dwordx4 v[34:35], v[18:21], off offset:256 sc1
	v_cvt_pk_bf16_f32 v10, v22, v23
	v_cvt_pk_bf16_f32 v11, v24, v25
	v_cvt_pk_bf16_f32 v12, v14, v15
	v_cvt_pk_bf16_f32 v13, v16, v17
	s_nop 1
	v_lshl_add_u64 v[18:19], v[144:145], 0, s[6:7]
	s_mov_b32 s6, 0x160000
	v_add_co_u32_e32 v14, vcc, s6, v144
	s_nop 1
	v_addc_co_u32_e32 v15, vcc, 0, v145, vcc
	global_store_dwordx4 v[14:15], v[10:13], off sc1
	v_cvt_pk_bf16_f32 v6, v6, v7
	v_cvt_pk_bf16_f32 v7, v8, v9
	v_cvt_pk_bf16_f32 v8, v2, v3
	v_cvt_pk_bf16_f32 v9, v4, v5
	global_store_dwordx4 v[18:19], v[6:9], off offset:256 sc1
	s_and_b64 vcc, exec, s[4:5]
	s_mov_b64 s[4:5], -1
	s_cbranch_vccnz .LBB0_1527

.LBB0_1542:
	s_mov_b64 s[6:7], s[76:77]
	s_mov_b32 s4, s3
	s_mov_b32 s5, -1
	s_getreg_b32 s8, hwreg(HW_REG_XCC_ID, 0, 4)
	s_nop 0
	v_mbcnt_lo_u32_b32 v0, s5, 0
	v_mbcnt_hi_u32_b32 v0, s5, v0
	v_lshl_add_u32 v0, s4, 6, v0
	s_waitcnt vmcnt(0)
	s_waitcnt vmcnt(0)
	v_cmp_eq_u32_e32 vcc, 0, v0
	s_barrier
	s_and_saveexec_b64 s[4:5], vcc
	s_cbranch_execz .LBB0_1594
	s_load_dwordx2 s[6:7], s[6:7], 0xb8
	v_mov_b32_e32 v0, 0
	v_mov_b32_e32 v2, 1
	s_waitcnt vmcnt(0) lgkmcnt(0)
	global_atomic_add v0, v2, s[6:7] offset:2048
.LBB0_1594:
	s_or_b64 exec, exec, s[4:5]
	s_sub_i32 s98, s96, s2
	s_sub_i32 s98, s98, 1
	v_writelane_b32 v255, s98, 54
	s_and_b32 s99, s98, 7
	v_writelane_b32 v255, s99, 55
	s_lshr_b32 s99, s98, 3
	v_writelane_b32 v255, s99, 56
	s_mov_b64 s[4:5], s[76:77]
	s_mov_b32 s36, s96
	s_mov_b32 s6, s3
	s_mov_b32 s7, -1
	s_waitcnt lgkmcnt(0)
	s_barrier
	s_andn2_b64 vcc, exec, s[0:1]
	v_mbcnt_lo_u32_b32 v0, s7, 0
	v_mbcnt_hi_u32_b32 v0, s7, v0
	v_lshl_add_u32 v16, s6, 6, v0
	s_nop 0
	s_nop 0
	v_readfirstlane_b32 s10, v16
	s_cbranch_vccnz .LBB0_1610
	v_lshlrev_b32_e32 v0, 4, v16
	v_add_u32_e32 v2, 0x2000, v0
	v_ashrrev_i32_e32 v3, 31, v2
	v_lshrrev_b32_e32 v3, 22, v3
	v_add_u32_e32 v3, v2, v3
	v_ashrrev_i32_e32 v10, 10, v3
	v_mul_i32_i24_e32 v4, 0x400, v10
	v_sub_u32_e32 v2, v2, v4
	v_lshrrev_b32_e32 v4, 4, v2
	v_bitop3_b32 v2, v4, v2, 32 bitop3:0x6c
	v_ashrrev_i32_e32 v4, 31, v2
	s_load_dwordx2 s[4:5], s[4:5], 0xb8
	v_lshrrev_b32_e32 v4, 26, v4
	v_add_u32_e32 v4, v2, v4
	v_ashrrev_i32_e32 v11, 6, v4
	v_and_b32_e32 v4, 0xc0, v4
	v_sub_u32_e32 v2, v2, v4
	v_lshlrev_b32_e32 v3, 5, v10
	v_ashrrev_i16_sdwa v2, v215, sext(v2) dst_sel:DWORD dst_unused:UNUSED_PAD src0_sel:DWORD src1_sel:BYTE_0
	s_waitcnt lgkmcnt(0)
	s_add_u32 s37, s4, 0x400000
	v_and_b32_e32 v3, 32, v3
	v_bfe_i32 v12, v2, 0, 16
	s_addc_u32 s60, s5, 0
	v_add_u32_e32 v2, v3, v12
	v_lshlrev_b32_e32 v3, 3, v10
	s_add_u32 s63, s4, 0x10500000
	v_and_b32_e32 v3, 0x1ffff0, v3
	s_addc_u32 s72, s5, 0
	s_ashr_i32 s12, s10, 6
	v_add_lshl_u32 v3, v11, v3, 11
	s_lshl_b32 s74, s25, 1
	v_readlane_b32 s0, v255, 6
	s_ashr_i32 s11, s10, 8
	s_lshl_b32 s73, s12, 10
	v_lshl_add_u32 v134, v2, 1, v3
	v_bfe_i32 v3, v16, 27, 1
	s_or_b32 s75, s74, 1
	v_readlane_b32 s1, v255, 7
	v_lshrrev_b32_e32 v3, 22, v3
	s_and_b64 s[0:1], s[0:1], exec
	v_add_u32_e32 v3, v0, v3
	s_cselect_b32 s0, s75, s74
	v_readlane_b32 s1, v255, 55
	v_and_b32_e32 v3, 0xfffffc00, v3
	s_mul_i32 s0, s0, s1
	v_readlane_b32 s1, v255, 56
	v_sub_u32_e32 v0, v0, v3
	s_add_i32 s0, s0, s1
	v_lshrrev_b32_e32 v3, 4, v0
	s_ashr_i32 s1, s0, 31
	v_bitop3_b32 v0, v3, v0, 32 bitop3:0x6c
	s_lshr_b32 s1, s1, 25
	v_ashrrev_i32_e32 v3, 31, v0
	s_add_i32 s1, s0, s1
	v_ashrrev_i32_e32 v2, 31, v16
	v_lshrrev_b32_e32 v3, 26, v3
	s_ashr_i32 s6, s1, 7
	v_lshrrev_b32_e32 v2, 26, v2
	v_add_u32_e32 v3, v0, v3
	s_lshl_b32 s6, s6, 3
	v_add_u32_e32 v2, v16, v2
	v_ashrrev_i32_e32 v14, 6, v3
	v_and_b32_e32 v3, 0xc0, v3
	s_sub_i32 s7, s25, s6
	v_ashrrev_i32_e32 v13, 6, v2
	v_sub_u32_e32 v0, v0, v3
	s_min_i32 s7, s7, 8
	v_lshlrev_b32_e32 v2, 5, v13
	v_ashrrev_i16_sdwa v0, v215, sext(v0) dst_sel:DWORD dst_unused:UNUSED_PAD src0_sel:DWORD src1_sel:BYTE_0
	s_abs_i32 s8, s7
	v_and_b32_e32 v2, 32, v2
	v_bfe_i32 v15, v0, 0, 16
	v_cvt_f32_u32_e32 v3, s8
	v_add_u32_e32 v0, v2, v15
	v_lshlrev_b32_e32 v2, 3, v13
	v_and_b32_e32 v2, 0x1ffff0, v2
	v_add_lshl_u32 v2, v14, v2, 11
	v_lshl_add_u32 v0, v0, 1, v2
	v_rcp_iflag_f32_e32 v2, v3
	s_sub_i32 s13, 0, s8
	s_and_b32 s1, s1, 0xffffff80
	s_sub_i32 s0, s0, s1
	v_mul_f32_e32 v2, 0x4f7ffffe, v2
	v_cvt_u32_f32_e32 v2, v2
	s_abs_i32 s9, s0
	s_xor_b32 s1, s0, s7
	s_ashr_i32 s1, s1, 31
	v_readfirstlane_b32 s16, v2
	s_mul_i32 s13, s13, s16
	s_mul_hi_u32 s13, s16, s13
	s_add_i32 s16, s16, s13
	s_mul_hi_u32 s13, s9, s16
	s_mul_i32 s16, s13, s8
	s_sub_i32 s9, s9, s16
	s_add_i32 s16, s13, 1
	s_sub_i32 s17, s9, s8
	s_cmp_ge_u32 s9, s8
	s_cselect_b32 s13, s16, s13
	s_cselect_b32 s9, s17, s9
	s_add_i32 s16, s13, 1
	s_cmp_ge_u32 s9, s8
	s_cselect_b32 s8, s16, s13
	s_xor_b32 s8, s8, s1
	s_sub_i32 s26, s8, s1
	s_mul_i32 s1, s26, s7
	s_sub_i32 s0, s0, s1
	s_add_i32 s6, s6, s0
	s_ashr_i32 s0, s6, 3
	s_add_i32 s0, s6, s0
	s_add_i32 s7, s0, 1
	s_and_b64 s[0:1], s[66:67], exec
	s_cselect_b32 s52, s7, s6
	s_ashr_i32 s53, s52, 31
	s_lshl_b64 s[0:1], s[52:53], 19
	s_add_u32 s56, s37, s0
	s_addc_u32 s57, s60, s1
	s_ashr_i32 s27, s26, 31
	s_lshl_b64 s[0:1], s[26:27], 19
	s_add_u32 s68, s63, s0
	s_addc_u32 s69, s72, s1
	s_add_i32 s53, s73, 0
	s_add_i32 m0, s53, 0x10000
	v_mov_b32_e32 v135, v1
	global_load_lds_dwordx4 v0, s[68:69]
	s_add_i32 m0, s53, 0x12000
	s_add_u32 s0, s68, 0x40000
	global_load_lds_dwordx4 v134, s[68:69]
	s_addc_u32 s1, s69, 0
	s_add_i32 m0, s53, 0x14000
	s_add_i32 s78, s53, 0x2000
	global_load_lds_dwordx4 v0, s[0:1]
	s_add_i32 m0, s53, 0x16000
	v_lshl_add_u64 v[8:9], s[68:69], 0, v[0:1]
	global_load_lds_dwordx4 v134, s[0:1]
	s_mov_b32 m0, s53
	s_add_u32 s0, s56, 0x40000
	global_load_lds_dwordx4 v0, s[56:57]
	s_mov_b32 m0, s78
	s_addc_u32 s1, s57, 0
	s_add_i32 s79, s53, 0x4000
	global_load_lds_dwordx4 v134, s[56:57]
	s_mov_b32 m0, s79
	s_add_i32 s80, s53, 0x6000
	global_load_lds_dwordx4 v0, s[0:1]
	s_mov_b32 m0, s80
	s_cmp_eq_u32 s11, 1
	global_load_lds_dwordx4 v134, s[0:1]
	v_lshl_add_u64 v[6:7], s[68:69], 0, v[134:135]
	v_lshl_add_u64 v[2:3], s[56:57], 0, v[0:1]
	s_cselect_b64 s[0:1], -1, 0
	s_cmp_lg_u32 s11, 1
	v_lshl_add_u64 v[4:5], s[56:57], 0, v[134:135]
	s_cbranch_scc1 .LBB0_1597
	s_barrier

.LBB0_1600:
	s_add_i32 s84, s84, 1
	s_mul_i32 s4, s84, s83
	s_mul_hi_u32 s5, s84, s36
	s_add_i32 s5, s5, s4
	s_mul_i32 s4, s84, s36
	v_readlane_b32 s18, v255, 54
	s_add_u32 s18, s4, s18
	s_addc_u32 s19, s5, s15
	v_mov_b64_e32 v[2:3], s[40:41]
	v_cmp_ge_i64_e32 vcc, s[18:19], v[2:3]
	v_cmp_lt_i64_e64 s[4:5], s[18:19], v[2:3]
	s_cbranch_vccnz .LBB0_1602
	s_ashr_i32 s12, s18, 31
	s_lshr_b32 s12, s12, 29
	s_add_i32 s12, s18, s12
	s_ashr_i32 s13, s12, 3
	s_and_b32 s12, s12, -8
	s_sub_i32 s12, s18, s12
	s_cmp_lt_i32 s12, 0
	s_cselect_b32 s16, s75, s74
	s_mul_i32 s12, s16, s12
	s_add_i32 s12, s12, s13
	s_ashr_i32 s13, s12, 31
	s_lshr_b32 s13, s13, 25
	s_add_i32 s13, s12, s13
	s_ashr_i32 s16, s13, 7
	s_lshl_b32 s16, s16, 3
	s_sub_i32 s17, s25, s16
	s_min_i32 s17, s17, 8
	s_abs_i32 s18, s17
	v_cvt_f32_u32_e32 v2, s18
	s_sub_i32 s20, 0, s18
	s_and_b32 s13, s13, 0xffffff80
	s_sub_i32 s13, s12, s13
	v_rcp_iflag_f32_e32 v2, v2
	s_abs_i32 s12, s13
	s_xor_b32 s19, s13, s17
	s_ashr_i32 s19, s19, 31
	v_mul_f32_e32 v2, 0x4f7ffffe, v2
	v_cvt_u32_f32_e32 v2, v2
	s_nop 0
	v_readfirstlane_b32 s21, v2
	s_mul_i32 s20, s20, s21
	s_mul_hi_u32 s20, s21, s20
	s_add_i32 s21, s21, s20
	s_mul_hi_u32 s20, s12, s21
	s_mul_i32 s21, s20, s18
	s_sub_i32 s12, s12, s21
	s_add_i32 s27, s20, 1
	s_sub_i32 s21, s12, s18
	s_cmp_ge_u32 s12, s18
	s_cselect_b32 s20, s27, s20
	s_cselect_b32 s12, s21, s12
	s_add_i32 s21, s20, 1
	s_cmp_ge_u32 s12, s18
	s_cselect_b32 s12, s21, s20
	s_xor_b32 s12, s12, s19
	s_sub_i32 s12, s12, s19
	s_mul_i32 s17, s12, s17
	s_sub_i32 s13, s13, s17
	s_add_i32 s16, s13, s16

.LBB0_1606:
	s_cmp_lg_u32 s84, 1
	s_cbranch_scc1 .Lw2_nowait
	s_cmp_lg_u32 s3, 0
	s_cbranch_scc1 .Lw2_bar
	s_load_dwordx2 s[98:99], s[76:77], 0xb8
	s_lshl_b32 vcc_lo, s96, 1
	v_readlane_b32 vcc_hi, v255, 26
	s_cmp_eq_u32 vcc_hi, -1
	s_cselect_b32 vcc_lo, s96, vcc_lo
	v_mov_b32_e32 v236, 0
	s_mov_b32 m0, 0
	s_waitcnt lgkmcnt(0)
.Lw2_spin:
	global_load_dword v237, v236, s[98:99] offset:2048 sc1
	s_waitcnt vmcnt(0)
	v_readfirstlane_b32 vcc_hi, v237
	s_cmp_ge_u32 vcc_hi, vcc_lo
	s_cbranch_scc1 .Lw2_done
	s_add_u32 m0, m0, 1
	s_cmp_gt_u32 m0, 0x100000
	s_cbranch_scc1 .Lw2_done
	s_sleep 1
	s_branch .Lw2_spin
.Lw2_done:
	buffer_inv sc1
	s_waitcnt vmcnt(0)
.Lw2_bar:
	s_barrier
.Lw2_nowait:
	v_lshl_add_u32 v142, s52, 8, v146
	v_lshl_or_b32 v140, s26, 6, v148
	v_ashrrev_i32_e32 v143, 31, v142
	v_ashrrev_i32_e32 v141, 31, v140
	v_lshlrev_b64 v[144:145], 13, v[142:143]
	v_lshl_add_u64 v[144:145], s[6:7], 0, v[144:145]
	v_lshlrev_b64 v[140:141], 1, v[140:141]
	v_lshl_add_u64 v[144:145], v[144:145], 0, v[140:141]
	global_load_dwordx2 v[160:161], v[144:145], off
	global_load_dwordx2 v[162:163], v[144:145], off offset:2048
	v_add_co_u32_e32 v220, vcc, 0x1000, v144
	s_nop 1
	v_addc_co_u32_e32 v221, vcc, 0, v145, vcc
	global_load_dwordx2 v[164:165], v[220:221], off
	global_load_dwordx2 v[166:167], v[220:221], off offset:2048
	v_add_co_u32_e32 v224, vcc, 0x20000, v144
	s_nop 1
	v_addc_co_u32_e32 v225, vcc, 0, v145, vcc
	global_load_dwordx2 v[168:169], v[224:225], off
	global_load_dwordx2 v[170:171], v[224:225], off offset:2048
	v_add_co_u32_e32 v226, vcc, 0x21000, v144
	s_nop 1
	v_addc_co_u32_e32 v227, vcc, 0, v145, vcc
	global_load_dwordx2 v[172:173], v[226:227], off
	global_load_dwordx2 v[174:175], v[226:227], off offset:2048
	v_add_co_u32_e32 v242, vcc, 0x40000, v144
	s_nop 1
	v_addc_co_u32_e32 v243, vcc, 0, v145, vcc
	global_load_dwordx2 v[176:177], v[242:243], off
	global_load_dwordx2 v[178:179], v[242:243], off offset:2048
	v_add_co_u32_e32 v244, vcc, 0x41000, v144
	s_nop 1
	v_addc_co_u32_e32 v245, vcc, 0, v145, vcc
	global_load_dwordx2 v[180:181], v[244:245], off
	global_load_dwordx2 v[182:183], v[244:245], off offset:2048
	v_add_co_u32_e32 v246, vcc, 0x60000, v144
	s_nop 1
	v_addc_co_u32_e32 v247, vcc, 0, v145, vcc
	global_load_dwordx2 v[184:185], v[246:247], off
	global_load_dwordx2 v[186:187], v[246:247], off offset:2048
	v_add_co_u32_e32 v248, vcc, 0x61000, v144
	s_nop 1
	v_addc_co_u32_e32 v249, vcc, 0, v145, vcc
	global_load_dwordx2 v[188:189], v[248:249], off
	global_load_dwordx2 v[190:191], v[248:249], off offset:2048
	v_add_co_u32_e32 v250, vcc, 0x100000, v144
	s_nop 1
	v_addc_co_u32_e32 v251, vcc, 0, v145, vcc
	global_load_dwordx2 v[192:193], v[250:251], off
	global_load_dwordx2 v[194:195], v[250:251], off offset:2048
	v_add_co_u32_e32 v252, vcc, 0x101000, v144
	s_nop 1
	v_addc_co_u32_e32 v253, vcc, 0, v145, vcc
	global_load_dwordx2 v[196:197], v[252:253], off
	global_load_dwordx2 v[198:199], v[252:253], off offset:2048
	v_add_co_u32_e32 v210, vcc, 0x120000, v144
	s_nop 1
	v_addc_co_u32_e32 v211, vcc, 0, v145, vcc
	global_load_dwordx2 v[200:201], v[210:211], off
	global_load_dwordx2 v[202:203], v[210:211], off offset:2048
	v_add_co_u32_e32 v220, vcc, 0x121000, v144
	s_nop 1
	v_addc_co_u32_e32 v221, vcc, 0, v145, vcc
	global_load_dwordx2 v[204:205], v[220:221], off
	global_load_dwordx2 v[206:207], v[220:221], off offset:2048
	v_add_co_u32_e32 v224, vcc, 0x140000, v144
	s_nop 1
	v_addc_co_u32_e32 v225, vcc, 0, v145, vcc
	global_load_dwordx2 v[208:209], v[224:225], off
	global_load_dwordx2 v[228:229], v[224:225], off offset:2048
	v_add_co_u32_e32 v226, vcc, 0x141000, v144
	s_nop 1
	v_addc_co_u32_e32 v227, vcc, 0, v145, vcc
	global_load_dwordx2 v[230:231], v[226:227], off
	global_load_dwordx2 v[232:233], v[226:227], off offset:2048
	v_add_co_u32_e32 v242, vcc, 0x160000, v144
	s_nop 1
	v_addc_co_u32_e32 v243, vcc, 0, v145, vcc
	global_load_dwordx2 v[234:235], v[242:243], off
	global_load_dwordx2 v[236:237], v[242:243], off offset:2048
	v_add_co_u32_e32 v244, vcc, 0x161000, v144
	s_nop 1
	v_addc_co_u32_e32 v245, vcc, 0, v145, vcc
	global_load_dwordx2 v[238:239], v[244:245], off
	global_load_dwordx2 v[240:241], v[244:245], off offset:2048
	s_nop 0
	s_nop 0
	v_mul_f32_e32 v127, 0xbfb8aa3b, v127
	v_exp_f32_e32 v127, v127
	v_mul_f32_e32 v126, 0xbfb8aa3b, v126
	v_mul_f32_e32 v122, 0xbfb8aa3b, v122
	v_exp_f32_e32 v126, v126
	v_add_f32_e32 v127, 1.0, v127
	v_rcp_f32_e32 v150, v127
	v_mul_f32_e32 v127, 0xbfb8aa3b, v128
	v_exp_f32_e32 v127, v127
	v_exp_f32_e32 v122, v122
	v_add_f32_e32 v126, 1.0, v126
	v_rcp_f32_e32 v126, v126
	v_add_f32_e32 v127, 1.0, v127
	v_rcp_f32_e32 v128, v127
	v_mul_f32_e32 v127, 0xbfb8aa3b, v129
	v_exp_f32_e32 v127, v127
	v_add_f32_e32 v122, 1.0, v122
	v_mul_f32_e32 v118, 0xbfb8aa3b, v118
	v_mul_f32_e32 v114, 0xbfb8aa3b, v114
	v_add_f32_e32 v127, 1.0, v127
	v_rcp_f32_e32 v154, v127
	v_rcp_f32_e32 v127, v122
	v_exp_f32_e32 v118, v118
	v_exp_f32_e32 v114, v114
	v_mul_f32_e32 v111, 0xbfb8aa3b, v111
	v_exp_f32_e32 v111, v111
	v_add_f32_e32 v118, 1.0, v118
	v_add_f32_e32 v114, 1.0, v114
	v_mul_f32_e32 v110, 0xbfb8aa3b, v110
	v_add_f32_e32 v111, 1.0, v111
	v_mul_f32_e32 v106, 0xbfb8aa3b, v106
	v_exp_f32_e32 v110, v110
	v_exp_f32_e32 v106, v106
	v_mul_f32_e32 v102, 0xbfb8aa3b, v102
	v_mul_f32_e32 v98, 0xbfb8aa3b, v98
	v_add_f32_e32 v110, 1.0, v110
	v_add_f32_e32 v106, 1.0, v106
	v_rcp_f32_e32 v110, v110
	v_exp_f32_e32 v102, v102
	v_exp_f32_e32 v98, v98
	v_mul_f32_e32 v95, 0xbfb8aa3b, v95
	v_exp_f32_e32 v95, v95
	v_add_f32_e32 v102, 1.0, v102
	v_add_f32_e32 v98, 1.0, v98
	v_mul_f32_e32 v94, 0xbfb8aa3b, v94
	v_add_f32_e32 v95, 1.0, v95
	v_mul_f32_e32 v90, 0xbfb8aa3b, v90
	v_exp_f32_e32 v94, v94
	v_exp_f32_e32 v90, v90
	v_mul_f32_e32 v86, 0xbfb8aa3b, v86
	v_mul_f32_e32 v82, 0xbfb8aa3b, v82
	v_add_f32_e32 v94, 1.0, v94
	v_add_f32_e32 v90, 1.0, v90
	v_rcp_f32_e32 v94, v94
	v_exp_f32_e32 v86, v86
	v_exp_f32_e32 v82, v82
	v_mul_f32_e32 v79, 0xbfb8aa3b, v79
	v_exp_f32_e32 v79, v79
	v_add_f32_e32 v86, 1.0, v86
	v_add_f32_e32 v82, 1.0, v82
	v_mul_f32_e32 v78, 0xbfb8aa3b, v78
	v_add_f32_e32 v79, 1.0, v79
	v_mul_f32_e32 v74, 0xbfb8aa3b, v74
	v_exp_f32_e32 v78, v78
	v_exp_f32_e32 v74, v74
	v_mul_f32_e32 v70, 0xbfb8aa3b, v70
	v_mul_f32_e32 v66, 0xbfb8aa3b, v66
	v_add_f32_e32 v78, 1.0, v78
	v_add_f32_e32 v74, 1.0, v74
	v_rcp_f32_e32 v78, v78
	v_exp_f32_e32 v70, v70
	v_exp_f32_e32 v66, v66
	v_mul_f32_e32 v63, 0xbfb8aa3b, v63
	v_exp_f32_e32 v63, v63
	v_add_f32_e32 v70, 1.0, v70
	v_add_f32_e32 v66, 1.0, v66
	v_mul_f32_e32 v62, 0xbfb8aa3b, v62
	v_add_f32_e32 v63, 1.0, v63
	s_waitcnt vmcnt(30)
	v_lshlrev_b32_e32 v158, 16, v160
	v_lshlrev_b32_e32 v159, 16, v162
	v_pk_mul_f32 v[126:127], v[126:127], v[158:159]
	v_mul_f32_e32 v58, 0xbfb8aa3b, v58
	v_add_f32_e32 v122, 0, v126
	v_add_f32_e32 v127, v122, v127
	v_mul_f32_e32 v122, 0xbfb8aa3b, v123
	v_exp_f32_e32 v122, v122
	v_and_b32_e32 v123, 0xffff0000, v162
	v_exp_f32_e32 v62, v62
	v_exp_f32_e32 v58, v58
	v_add_f32_e32 v122, 1.0, v122
	v_rcp_f32_e32 v151, v122
	v_and_b32_e32 v122, 0xffff0000, v160
	v_add_f32_e32 v62, 1.0, v62
	v_add_f32_e32 v58, 1.0, v58
	v_pk_mul_f32 v[122:123], v[150:151], v[122:123]
	v_rcp_f32_e32 v62, v62
	v_add_f32_e32 v122, 0, v122
	v_add_f32_e32 v152, v122, v123
	v_mul_f32_e32 v122, 0xbfb8aa3b, v124
	v_exp_f32_e32 v122, v122
	v_lshlrev_b32_e32 v123, 16, v163
	v_add_co_u32_e32 v124, vcc, s44, v144
	v_add_f32_e32 v122, 1.0, v122
	v_rcp_f32_e32 v129, v122
	v_lshlrev_b32_e32 v122, 16, v161
	v_mul_f32_e32 v54, 0xbfb8aa3b, v54
	v_mul_f32_e32 v50, 0xbfb8aa3b, v50
	v_pk_mul_f32 v[122:123], v[128:129], v[122:123]
	v_rcp_f32_e32 v128, v118
	v_add_f32_e32 v122, 0, v122
	v_add_f32_e32 v151, v122, v123
	v_mul_f32_e32 v122, 0xbfb8aa3b, v125
	v_exp_f32_e32 v122, v122
	v_and_b32_e32 v123, 0xffff0000, v163
	v_addc_co_u32_e32 v125, vcc, 0, v145, vcc
	v_add_f32_e32 v122, 1.0, v122
	v_rcp_f32_e32 v155, v122
	v_and_b32_e32 v122, 0xffff0000, v161
	v_rcp_f32_e32 v129, v114
	v_mul_f32_e32 v118, 0xbfb8aa3b, v119
	v_pk_mul_f32 v[122:123], v[154:155], v[122:123]
	v_exp_f32_e32 v118, v118
	v_add_f32_e32 v122, 0, v122
	v_add_f32_e32 v150, v122, v123
	s_nop 0
	v_add_f32_e32 v118, 1.0, v118
	s_nop 0
	v_rcp_f32_e32 v126, v118
	v_mul_f32_e32 v118, 0xbfb8aa3b, v120
	v_exp_f32_e32 v118, v118
	v_exp_f32_e32 v54, v54
	v_exp_f32_e32 v50, v50
	v_mul_f32_e32 v47, 0xbfb8aa3b, v47
	v_add_f32_e32 v118, 1.0, v118
	v_rcp_f32_e32 v120, v118
	v_mul_f32_e32 v118, 0xbfb8aa3b, v121
	v_exp_f32_e32 v118, v118
	v_add_f32_e32 v54, 1.0, v54
	v_add_f32_e32 v50, 1.0, v50
	v_exp_f32_e32 v47, v47
	v_add_f32_e32 v118, 1.0, v118
	v_rcp_f32_e32 v118, v118
	v_mul_f32_e32 v46, 0xbfb8aa3b, v46
	v_add_f32_e32 v47, 1.0, v47
	v_mul_f32_e32 v42, 0xbfb8aa3b, v42
	v_exp_f32_e32 v46, v46
	v_exp_f32_e32 v42, v42
	v_mul_f32_e32 v38, 0xbfb8aa3b, v38
	v_mul_f32_e32 v34, 0xbfb8aa3b, v34
	v_add_f32_e32 v46, 1.0, v46
	v_add_f32_e32 v42, 1.0, v42
	v_rcp_f32_e32 v46, v46
	v_exp_f32_e32 v38, v38
	v_exp_f32_e32 v34, v34
	v_mul_f32_e32 v31, 0xbfb8aa3b, v31
	v_exp_f32_e32 v31, v31
	v_add_f32_e32 v38, 1.0, v38
	v_add_f32_e32 v34, 1.0, v34
	v_mul_f32_e32 v30, 0xbfb8aa3b, v30
	v_add_f32_e32 v31, 1.0, v31
	v_mul_f32_e32 v26, 0xbfb8aa3b, v26
	v_exp_f32_e32 v30, v30
	v_exp_f32_e32 v26, v26
	v_mul_f32_e32 v22, 0xbfb8aa3b, v22
	v_mul_f32_e32 v18, 0xbfb8aa3b, v18
	v_add_f32_e32 v30, 1.0, v30
	v_add_f32_e32 v26, 1.0, v26
	v_rcp_f32_e32 v30, v30
	v_exp_f32_e32 v22, v22
	v_exp_f32_e32 v18, v18
	v_mul_f32_e32 v15, 0xbfb8aa3b, v15
	v_exp_f32_e32 v15, v15
	v_add_f32_e32 v22, 1.0, v22
	v_add_f32_e32 v18, 1.0, v18
	v_mul_f32_e32 v14, 0xbfb8aa3b, v14
	v_add_f32_e32 v15, 1.0, v15
	v_mul_f32_e32 v10, 0xbfb8aa3b, v10
	v_exp_f32_e32 v14, v14
	v_exp_f32_e32 v10, v10
	v_mul_f32_e32 v6, 0xbfb8aa3b, v6
	v_mul_f32_e32 v2, 0xbfb8aa3b, v2
	v_add_f32_e32 v14, 1.0, v14
	v_add_f32_e32 v10, 1.0, v10
	v_rcp_f32_e32 v14, v14
	v_exp_f32_e32 v6, v6
	v_exp_f32_e32 v2, v2
	s_mov_b64 s[26:27], -1
	v_add_f32_e32 v6, 1.0, v6
	v_add_f32_e32 v2, 1.0, v2
	s_waitcnt vmcnt(29)
	v_lshlrev_b32_e32 v144, 16, v164
	s_waitcnt vmcnt(28)
	v_lshlrev_b32_e32 v145, 16, v166
	v_pk_mul_f32 v[128:129], v[128:129], v[144:145]
	s_nop 0
	v_add_f32_e32 v114, v127, v128
	v_add_f32_e32 v128, v114, v129
	v_mul_f32_e32 v114, 0xbfb8aa3b, v115
	v_exp_f32_e32 v114, v114
	v_and_b32_e32 v115, 0xffff0000, v166
	v_add_f32_e32 v114, 1.0, v114
	v_rcp_f32_e32 v127, v114
	v_and_b32_e32 v114, 0xffff0000, v164
	v_pk_mul_f32 v[114:115], v[126:127], v[114:115]
	s_nop 0
	v_add_f32_e32 v114, v152, v114
	v_add_f32_e32 v122, v114, v115
	v_mul_f32_e32 v114, 0xbfb8aa3b, v116
	v_exp_f32_e32 v114, v114
	v_lshlrev_b32_e32 v115, 16, v167
	v_add_f32_e32 v114, 1.0, v114
	v_rcp_f32_e32 v121, v114
	v_lshlrev_b32_e32 v114, 16, v165
	v_pk_mul_f32 v[114:115], v[120:121], v[114:115]
	s_nop 0
	v_add_f32_e32 v114, v151, v114
	v_add_f32_e32 v116, v114, v115
	v_mul_f32_e32 v114, 0xbfb8aa3b, v117
	v_exp_f32_e32 v114, v114
	v_and_b32_e32 v115, 0xffff0000, v167
	v_add_f32_e32 v114, 1.0, v114
	v_rcp_f32_e32 v119, v114
	v_and_b32_e32 v114, 0xffff0000, v165
	v_pk_mul_f32 v[114:115], v[118:119], v[114:115]
	s_nop 0
	v_add_f32_e32 v114, v150, v114
	v_add_f32_e32 v115, v114, v115
	v_cvt_pk_bf16_f32 v114, v128, v122
	v_cvt_pk_bf16_f32 v115, v116, v115
	v_lshlrev_b64 v[116:117], 11, v[142:143]
	v_lshl_add_u64 v[116:117], s[8:9], 0, v[116:117]
	v_lshl_add_u64 v[116:117], v[116:117], 0, v[140:141]
	global_store_dwordx2 v[116:117], v[114:115], off
	v_or_b32_e32 v114, 16, v142
	v_ashrrev_i32_e32 v115, 31, v114
	v_lshlrev_b64 v[116:117], 13, v[114:115]
	v_lshl_add_u64 v[116:117], s[6:7], 0, v[116:117]
	v_lshl_add_u64 v[116:117], v[116:117], 0, v[140:141]
	s_nop 0
	s_nop 0
	v_rcp_f32_e32 v118, v111
	v_mul_f32_e32 v111, 0xbfb8aa3b, v112
	v_exp_f32_e32 v111, v111
	s_waitcnt vmcnt(28)
	v_lshlrev_b32_e32 v126, 16, v168
	v_add_f32_e32 v111, 1.0, v111
	v_rcp_f32_e32 v112, v111
	v_mul_f32_e32 v111, 0xbfb8aa3b, v113
	v_exp_f32_e32 v111, v111
	s_waitcnt vmcnt(27)
	v_lshlrev_b32_e32 v127, 16, v170
	v_add_f32_e32 v111, 1.0, v111
	v_rcp_f32_e32 v122, v111
	v_rcp_f32_e32 v111, v106
	s_nop 0
	v_pk_mul_f32 v[110:111], v[110:111], v[126:127]
	s_nop 0
	v_add_f32_e32 v106, 0, v110
	v_add_f32_e32 v111, v106, v111
	v_mul_f32_e32 v106, 0xbfb8aa3b, v107
	v_exp_f32_e32 v106, v106
	v_and_b32_e32 v107, 0xffff0000, v170
	v_add_f32_e32 v106, 1.0, v106
	v_rcp_f32_e32 v119, v106
	v_and_b32_e32 v106, 0xffff0000, v168
	v_pk_mul_f32 v[106:107], v[118:119], v[106:107]
	s_nop 0
	v_add_f32_e32 v106, 0, v106
	v_add_f32_e32 v120, v106, v107
	v_mul_f32_e32 v106, 0xbfb8aa3b, v108
	v_exp_f32_e32 v106, v106
	v_lshlrev_b32_e32 v107, 16, v171
	v_add_co_u32_e32 v108, vcc, s44, v116
	v_add_f32_e32 v106, 1.0, v106
	v_rcp_f32_e32 v113, v106
	v_lshlrev_b32_e32 v106, 16, v169
	v_pk_mul_f32 v[106:107], v[112:113], v[106:107]
	s_nop 0
	v_add_f32_e32 v106, 0, v106
	v_add_f32_e32 v119, v106, v107
	v_mul_f32_e32 v106, 0xbfb8aa3b, v109
	v_exp_f32_e32 v106, v106
	v_and_b32_e32 v107, 0xffff0000, v171
	v_addc_co_u32_e32 v109, vcc, 0, v117, vcc
	v_add_f32_e32 v106, 1.0, v106
	v_rcp_f32_e32 v123, v106
	v_and_b32_e32 v106, 0xffff0000, v169
	v_rcp_f32_e32 v112, v102
	v_rcp_f32_e32 v113, v98
	v_pk_mul_f32 v[106:107], v[122:123], v[106:107]
	v_mul_f32_e32 v102, 0xbfb8aa3b, v103
	v_add_f32_e32 v106, 0, v106
	v_add_f32_e32 v118, v106, v107
	s_nop 0
	v_exp_f32_e32 v102, v102
	s_nop 0
	v_add_f32_e32 v102, 1.0, v102
	v_rcp_f32_e32 v110, v102
	v_mul_f32_e32 v102, 0xbfb8aa3b, v104
	v_exp_f32_e32 v102, v102
	s_waitcnt vmcnt(26)
	v_lshlrev_b32_e32 v116, 16, v172
	v_add_f32_e32 v102, 1.0, v102
	s_waitcnt vmcnt(25)
	v_lshlrev_b32_e32 v117, 16, v174
	v_pk_mul_f32 v[112:113], v[112:113], v[116:117]
	v_rcp_f32_e32 v104, v102
	v_add_f32_e32 v98, v111, v112
	v_add_f32_e32 v112, v98, v113
	v_mul_f32_e32 v98, 0xbfb8aa3b, v99
	v_exp_f32_e32 v98, v98
	v_and_b32_e32 v99, 0xffff0000, v174
	v_mul_f32_e32 v102, 0xbfb8aa3b, v105
	v_exp_f32_e32 v102, v102
	v_add_f32_e32 v98, 1.0, v98
	v_rcp_f32_e32 v111, v98
	v_and_b32_e32 v98, 0xffff0000, v172
	v_add_f32_e32 v102, 1.0, v102
	v_rcp_f32_e32 v102, v102
	v_pk_mul_f32 v[98:99], v[110:111], v[98:99]
	s_nop 0
	v_add_f32_e32 v98, v120, v98
	v_add_f32_e32 v106, v98, v99
	v_mul_f32_e32 v98, 0xbfb8aa3b, v100
	v_exp_f32_e32 v98, v98
	v_lshlrev_b32_e32 v99, 16, v175
	v_add_f32_e32 v98, 1.0, v98
	v_rcp_f32_e32 v105, v98
	v_lshlrev_b32_e32 v98, 16, v173
	v_pk_mul_f32 v[98:99], v[104:105], v[98:99]
	s_nop 0
	v_add_f32_e32 v98, v119, v98
	v_add_f32_e32 v100, v98, v99
	v_mul_f32_e32 v98, 0xbfb8aa3b, v101
	v_exp_f32_e32 v98, v98
	v_and_b32_e32 v99, 0xffff0000, v175
	v_add_f32_e32 v98, 1.0, v98
	v_rcp_f32_e32 v103, v98
	v_and_b32_e32 v98, 0xffff0000, v173
	v_pk_mul_f32 v[98:99], v[102:103], v[98:99]
	s_nop 0
	v_add_f32_e32 v98, v118, v98
	v_add_f32_e32 v99, v98, v99
	v_cvt_pk_bf16_f32 v98, v112, v106
	v_cvt_pk_bf16_f32 v99, v100, v99
	v_lshlrev_b64 v[100:101], 11, v[114:115]
	v_lshl_add_u64 v[100:101], s[8:9], 0, v[100:101]
	v_lshl_add_u64 v[100:101], v[100:101], 0, v[140:141]
	global_store_dwordx2 v[100:101], v[98:99], off
	v_or_b32_e32 v98, 32, v142
	v_ashrrev_i32_e32 v99, 31, v98
	v_lshlrev_b64 v[100:101], 13, v[98:99]
	v_lshl_add_u64 v[100:101], s[6:7], 0, v[100:101]
	v_lshl_add_u64 v[100:101], v[100:101], 0, v[140:141]
	s_nop 0
	s_nop 0
	v_rcp_f32_e32 v102, v95
	v_mul_f32_e32 v95, 0xbfb8aa3b, v96
	v_exp_f32_e32 v95, v95
	s_waitcnt vmcnt(25)
	v_lshlrev_b32_e32 v110, 16, v176
	v_add_f32_e32 v95, 1.0, v95
	v_rcp_f32_e32 v96, v95
	v_mul_f32_e32 v95, 0xbfb8aa3b, v97
	v_exp_f32_e32 v95, v95
	s_waitcnt vmcnt(24)
	v_lshlrev_b32_e32 v111, 16, v178
	v_add_f32_e32 v95, 1.0, v95
	v_rcp_f32_e32 v106, v95
	v_rcp_f32_e32 v95, v90
	s_nop 0
	v_pk_mul_f32 v[94:95], v[94:95], v[110:111]
	s_nop 0
	v_add_f32_e32 v90, 0, v94
	v_add_f32_e32 v95, v90, v95
	v_mul_f32_e32 v90, 0xbfb8aa3b, v91
	v_exp_f32_e32 v90, v90
	v_and_b32_e32 v91, 0xffff0000, v178
	v_add_f32_e32 v90, 1.0, v90
	v_rcp_f32_e32 v103, v90
	v_and_b32_e32 v90, 0xffff0000, v176
	v_pk_mul_f32 v[90:91], v[102:103], v[90:91]
	s_nop 0
	v_add_f32_e32 v90, 0, v90
	v_add_f32_e32 v104, v90, v91
	v_mul_f32_e32 v90, 0xbfb8aa3b, v92
	v_exp_f32_e32 v90, v90
	v_lshlrev_b32_e32 v91, 16, v179
	v_add_co_u32_e32 v92, vcc, s44, v100
	v_add_f32_e32 v90, 1.0, v90
	v_rcp_f32_e32 v97, v90
	v_lshlrev_b32_e32 v90, 16, v177
	v_pk_mul_f32 v[90:91], v[96:97], v[90:91]
	s_nop 0
	v_add_f32_e32 v90, 0, v90
	v_add_f32_e32 v103, v90, v91
	v_mul_f32_e32 v90, 0xbfb8aa3b, v93
	v_exp_f32_e32 v90, v90
	v_and_b32_e32 v91, 0xffff0000, v179
	v_addc_co_u32_e32 v93, vcc, 0, v101, vcc
	v_add_f32_e32 v90, 1.0, v90
	v_rcp_f32_e32 v107, v90
	v_and_b32_e32 v90, 0xffff0000, v177
	v_rcp_f32_e32 v96, v86
	v_rcp_f32_e32 v97, v82
	v_pk_mul_f32 v[90:91], v[106:107], v[90:91]
	v_mul_f32_e32 v86, 0xbfb8aa3b, v87
	v_add_f32_e32 v90, 0, v90
	v_add_f32_e32 v102, v90, v91
	s_nop 0
	v_exp_f32_e32 v86, v86
	s_nop 0
	v_add_f32_e32 v86, 1.0, v86
	v_rcp_f32_e32 v94, v86
	v_mul_f32_e32 v86, 0xbfb8aa3b, v88
	v_exp_f32_e32 v86, v86
	s_waitcnt vmcnt(23)
	v_lshlrev_b32_e32 v100, 16, v180
	v_add_f32_e32 v86, 1.0, v86
	s_waitcnt vmcnt(22)
	v_lshlrev_b32_e32 v101, 16, v182
	v_pk_mul_f32 v[96:97], v[96:97], v[100:101]
	v_rcp_f32_e32 v88, v86
	v_add_f32_e32 v82, v95, v96
	v_add_f32_e32 v96, v82, v97
	v_mul_f32_e32 v82, 0xbfb8aa3b, v83
	v_exp_f32_e32 v82, v82
	v_and_b32_e32 v83, 0xffff0000, v182
	v_mul_f32_e32 v86, 0xbfb8aa3b, v89
	v_exp_f32_e32 v86, v86
	v_add_f32_e32 v82, 1.0, v82
	v_rcp_f32_e32 v95, v82
	v_and_b32_e32 v82, 0xffff0000, v180
	v_add_f32_e32 v86, 1.0, v86
	v_rcp_f32_e32 v86, v86
	v_pk_mul_f32 v[82:83], v[94:95], v[82:83]
	s_nop 0
	v_add_f32_e32 v82, v104, v82
	v_add_f32_e32 v90, v82, v83
	v_mul_f32_e32 v82, 0xbfb8aa3b, v84
	v_exp_f32_e32 v82, v82
	v_lshlrev_b32_e32 v83, 16, v183
	v_add_f32_e32 v82, 1.0, v82
	v_rcp_f32_e32 v89, v82
	v_lshlrev_b32_e32 v82, 16, v181
	v_pk_mul_f32 v[82:83], v[88:89], v[82:83]
	s_nop 0
	v_add_f32_e32 v82, v103, v82
	v_add_f32_e32 v84, v82, v83
	v_mul_f32_e32 v82, 0xbfb8aa3b, v85
	v_exp_f32_e32 v82, v82
	v_and_b32_e32 v83, 0xffff0000, v183
	v_add_f32_e32 v82, 1.0, v82
	v_rcp_f32_e32 v87, v82
	v_and_b32_e32 v82, 0xffff0000, v181
	v_pk_mul_f32 v[82:83], v[86:87], v[82:83]
	s_nop 0
	v_add_f32_e32 v82, v102, v82
	v_add_f32_e32 v83, v82, v83
	v_cvt_pk_bf16_f32 v82, v96, v90
	v_cvt_pk_bf16_f32 v83, v84, v83
	v_lshlrev_b64 v[84:85], 11, v[98:99]
	v_lshl_add_u64 v[84:85], s[8:9], 0, v[84:85]
	v_lshl_add_u64 v[84:85], v[84:85], 0, v[140:141]
	global_store_dwordx2 v[84:85], v[82:83], off
	v_or_b32_e32 v82, 48, v142
	v_ashrrev_i32_e32 v83, 31, v82
	v_lshlrev_b64 v[84:85], 13, v[82:83]
	v_lshl_add_u64 v[84:85], s[6:7], 0, v[84:85]
	v_lshl_add_u64 v[84:85], v[84:85], 0, v[140:141]
	s_nop 0
	s_nop 0
	v_rcp_f32_e32 v86, v79
	v_mul_f32_e32 v79, 0xbfb8aa3b, v80
	v_exp_f32_e32 v79, v79
	s_waitcnt vmcnt(22)
	v_lshlrev_b32_e32 v94, 16, v184
	v_add_f32_e32 v79, 1.0, v79
	v_rcp_f32_e32 v80, v79
	v_mul_f32_e32 v79, 0xbfb8aa3b, v81
	v_exp_f32_e32 v79, v79
	s_waitcnt vmcnt(21)
	v_lshlrev_b32_e32 v95, 16, v186
	v_add_f32_e32 v79, 1.0, v79
	v_rcp_f32_e32 v90, v79
	v_rcp_f32_e32 v79, v74
	s_nop 0
	v_pk_mul_f32 v[78:79], v[78:79], v[94:95]
	s_nop 0
	v_add_f32_e32 v74, 0, v78
	v_add_f32_e32 v79, v74, v79
	v_mul_f32_e32 v74, 0xbfb8aa3b, v75
	v_exp_f32_e32 v74, v74
	v_and_b32_e32 v75, 0xffff0000, v186
	v_add_f32_e32 v74, 1.0, v74
	v_rcp_f32_e32 v87, v74
	v_and_b32_e32 v74, 0xffff0000, v184
	v_pk_mul_f32 v[74:75], v[86:87], v[74:75]
	s_nop 0
	v_add_f32_e32 v74, 0, v74
	v_add_f32_e32 v88, v74, v75
	v_mul_f32_e32 v74, 0xbfb8aa3b, v76
	v_exp_f32_e32 v74, v74
	v_lshlrev_b32_e32 v75, 16, v187
	v_add_co_u32_e32 v76, vcc, s44, v84
	v_add_f32_e32 v74, 1.0, v74
	v_rcp_f32_e32 v81, v74
	v_lshlrev_b32_e32 v74, 16, v185
	v_pk_mul_f32 v[74:75], v[80:81], v[74:75]
	s_nop 0
	v_add_f32_e32 v74, 0, v74
	v_add_f32_e32 v87, v74, v75
	v_mul_f32_e32 v74, 0xbfb8aa3b, v77
	v_exp_f32_e32 v74, v74
	v_and_b32_e32 v75, 0xffff0000, v187
	v_addc_co_u32_e32 v77, vcc, 0, v85, vcc
	v_add_f32_e32 v74, 1.0, v74
	v_rcp_f32_e32 v91, v74
	v_and_b32_e32 v74, 0xffff0000, v185
	v_rcp_f32_e32 v80, v70
	v_rcp_f32_e32 v81, v66
	v_pk_mul_f32 v[74:75], v[90:91], v[74:75]
	v_mul_f32_e32 v70, 0xbfb8aa3b, v71
	v_add_f32_e32 v74, 0, v74
	v_add_f32_e32 v86, v74, v75
	s_nop 0
	v_exp_f32_e32 v70, v70
	s_nop 0
	v_add_f32_e32 v70, 1.0, v70
	v_rcp_f32_e32 v78, v70
	v_mul_f32_e32 v70, 0xbfb8aa3b, v72
	v_exp_f32_e32 v70, v70
	s_waitcnt vmcnt(20)
	v_lshlrev_b32_e32 v84, 16, v188
	v_add_f32_e32 v70, 1.0, v70
	s_waitcnt vmcnt(19)
	v_lshlrev_b32_e32 v85, 16, v190
	v_pk_mul_f32 v[80:81], v[80:81], v[84:85]
	v_rcp_f32_e32 v72, v70
	v_add_f32_e32 v66, v79, v80
	v_add_f32_e32 v80, v66, v81
	v_mul_f32_e32 v66, 0xbfb8aa3b, v67
	v_exp_f32_e32 v66, v66
	v_and_b32_e32 v67, 0xffff0000, v190
	v_mul_f32_e32 v70, 0xbfb8aa3b, v73
	v_exp_f32_e32 v70, v70
	v_add_f32_e32 v66, 1.0, v66
	v_rcp_f32_e32 v79, v66
	v_and_b32_e32 v66, 0xffff0000, v188
	v_add_f32_e32 v70, 1.0, v70
	v_rcp_f32_e32 v70, v70
	v_pk_mul_f32 v[66:67], v[78:79], v[66:67]
	s_nop 0
	v_add_f32_e32 v66, v88, v66
	v_add_f32_e32 v74, v66, v67
	v_mul_f32_e32 v66, 0xbfb8aa3b, v68
	v_exp_f32_e32 v66, v66
	v_lshlrev_b32_e32 v67, 16, v191
	v_add_f32_e32 v66, 1.0, v66
	v_rcp_f32_e32 v73, v66
	v_lshlrev_b32_e32 v66, 16, v189
	v_pk_mul_f32 v[66:67], v[72:73], v[66:67]
	s_nop 0
	v_add_f32_e32 v66, v87, v66
	v_add_f32_e32 v68, v66, v67
	v_mul_f32_e32 v66, 0xbfb8aa3b, v69
	v_exp_f32_e32 v66, v66
	v_and_b32_e32 v67, 0xffff0000, v191
	v_add_f32_e32 v66, 1.0, v66
	v_rcp_f32_e32 v71, v66
	v_and_b32_e32 v66, 0xffff0000, v189
	v_pk_mul_f32 v[66:67], v[70:71], v[66:67]
	s_nop 0
	v_add_f32_e32 v66, v86, v66
	v_add_f32_e32 v67, v66, v67
	v_cvt_pk_bf16_f32 v66, v80, v74
	v_cvt_pk_bf16_f32 v67, v68, v67
	v_lshlrev_b64 v[68:69], 11, v[82:83]
	v_lshl_add_u64 v[68:69], s[8:9], 0, v[68:69]
	v_lshl_add_u64 v[68:69], v[68:69], 0, v[140:141]
	global_store_dwordx2 v[68:69], v[66:67], off
	v_add_u32_e32 v66, 0x80, v142
	v_ashrrev_i32_e32 v67, 31, v66
	v_lshlrev_b64 v[68:69], 13, v[66:67]
	v_lshl_add_u64 v[68:69], s[6:7], 0, v[68:69]
	v_lshl_add_u64 v[68:69], v[68:69], 0, v[140:141]
	s_nop 0
	s_nop 0
	v_rcp_f32_e32 v70, v63
	v_mul_f32_e32 v63, 0xbfb8aa3b, v64
	v_exp_f32_e32 v63, v63
	s_waitcnt vmcnt(19)
	v_lshlrev_b32_e32 v78, 16, v192
	v_add_f32_e32 v63, 1.0, v63
	v_rcp_f32_e32 v64, v63
	v_mul_f32_e32 v63, 0xbfb8aa3b, v65
	v_exp_f32_e32 v63, v63
	s_waitcnt vmcnt(18)
	v_lshlrev_b32_e32 v79, 16, v194
	v_add_f32_e32 v63, 1.0, v63
	v_rcp_f32_e32 v74, v63
	v_rcp_f32_e32 v63, v58
	s_nop 0
	v_pk_mul_f32 v[62:63], v[62:63], v[78:79]
	s_nop 0
	v_add_f32_e32 v58, 0, v62
	v_add_f32_e32 v63, v58, v63
	v_mul_f32_e32 v58, 0xbfb8aa3b, v59
	v_exp_f32_e32 v58, v58
	v_and_b32_e32 v59, 0xffff0000, v194
	v_add_f32_e32 v58, 1.0, v58
	v_rcp_f32_e32 v71, v58
	v_and_b32_e32 v58, 0xffff0000, v192
	v_pk_mul_f32 v[58:59], v[70:71], v[58:59]
	s_nop 0
	v_add_f32_e32 v58, 0, v58
	v_add_f32_e32 v72, v58, v59
	v_mul_f32_e32 v58, 0xbfb8aa3b, v60
	v_exp_f32_e32 v58, v58
	v_lshlrev_b32_e32 v59, 16, v195
	v_add_co_u32_e32 v60, vcc, s44, v68
	v_add_f32_e32 v58, 1.0, v58
	v_rcp_f32_e32 v65, v58
	v_lshlrev_b32_e32 v58, 16, v193
	v_pk_mul_f32 v[58:59], v[64:65], v[58:59]
	s_nop 0
	v_add_f32_e32 v58, 0, v58
	v_add_f32_e32 v71, v58, v59
	v_mul_f32_e32 v58, 0xbfb8aa3b, v61
	v_exp_f32_e32 v58, v58
	v_and_b32_e32 v59, 0xffff0000, v195
	v_addc_co_u32_e32 v61, vcc, 0, v69, vcc
	v_add_f32_e32 v58, 1.0, v58
	v_rcp_f32_e32 v75, v58
	v_and_b32_e32 v58, 0xffff0000, v193
	v_rcp_f32_e32 v64, v54
	v_rcp_f32_e32 v65, v50
	v_pk_mul_f32 v[58:59], v[74:75], v[58:59]
	v_mul_f32_e32 v54, 0xbfb8aa3b, v55
	v_add_f32_e32 v58, 0, v58
	v_add_f32_e32 v70, v58, v59
	s_nop 0
	v_exp_f32_e32 v54, v54
	s_nop 0
	v_add_f32_e32 v54, 1.0, v54
	v_rcp_f32_e32 v62, v54
	v_mul_f32_e32 v54, 0xbfb8aa3b, v56
	v_exp_f32_e32 v54, v54
	s_waitcnt vmcnt(17)
	v_lshlrev_b32_e32 v68, 16, v196
	v_add_f32_e32 v54, 1.0, v54
	s_waitcnt vmcnt(16)
	v_lshlrev_b32_e32 v69, 16, v198
	v_pk_mul_f32 v[64:65], v[64:65], v[68:69]
	v_rcp_f32_e32 v56, v54
	v_add_f32_e32 v50, v63, v64
	v_add_f32_e32 v64, v50, v65
	v_mul_f32_e32 v50, 0xbfb8aa3b, v51
	v_exp_f32_e32 v50, v50
	v_and_b32_e32 v51, 0xffff0000, v198
	v_mul_f32_e32 v54, 0xbfb8aa3b, v57
	v_exp_f32_e32 v54, v54
	v_add_f32_e32 v50, 1.0, v50
	v_rcp_f32_e32 v63, v50
	v_and_b32_e32 v50, 0xffff0000, v196
	v_add_f32_e32 v54, 1.0, v54
	v_rcp_f32_e32 v54, v54
	v_pk_mul_f32 v[50:51], v[62:63], v[50:51]
	s_nop 0
	v_add_f32_e32 v50, v72, v50
	v_add_f32_e32 v58, v50, v51
	v_mul_f32_e32 v50, 0xbfb8aa3b, v52
	v_exp_f32_e32 v50, v50
	v_lshlrev_b32_e32 v51, 16, v199
	v_add_f32_e32 v50, 1.0, v50
	v_rcp_f32_e32 v57, v50
	v_lshlrev_b32_e32 v50, 16, v197
	v_pk_mul_f32 v[50:51], v[56:57], v[50:51]
	s_nop 0
	v_add_f32_e32 v50, v71, v50
	v_add_f32_e32 v52, v50, v51
	v_mul_f32_e32 v50, 0xbfb8aa3b, v53
	v_exp_f32_e32 v50, v50
	v_and_b32_e32 v51, 0xffff0000, v199
	v_add_f32_e32 v50, 1.0, v50
	v_rcp_f32_e32 v55, v50
	v_and_b32_e32 v50, 0xffff0000, v197
	v_pk_mul_f32 v[50:51], v[54:55], v[50:51]
	s_nop 0
	v_add_f32_e32 v50, v70, v50
	v_add_f32_e32 v51, v50, v51
	v_cvt_pk_bf16_f32 v50, v64, v58
	v_cvt_pk_bf16_f32 v51, v52, v51
	v_lshlrev_b64 v[52:53], 11, v[66:67]
	v_lshl_add_u64 v[52:53], s[8:9], 0, v[52:53]
	v_lshl_add_u64 v[52:53], v[52:53], 0, v[140:141]
	global_store_dwordx2 v[52:53], v[50:51], off
	v_add_u32_e32 v50, 0x90, v142
	v_ashrrev_i32_e32 v51, 31, v50
	v_lshlrev_b64 v[52:53], 13, v[50:51]
	v_lshl_add_u64 v[52:53], s[6:7], 0, v[52:53]
	v_lshl_add_u64 v[52:53], v[52:53], 0, v[140:141]
	s_nop 0
	s_nop 0
	v_rcp_f32_e32 v54, v47
	v_mul_f32_e32 v47, 0xbfb8aa3b, v48
	v_exp_f32_e32 v47, v47
	s_waitcnt vmcnt(16)
	v_lshlrev_b32_e32 v62, 16, v200
	v_add_f32_e32 v47, 1.0, v47
	v_rcp_f32_e32 v48, v47
	v_mul_f32_e32 v47, 0xbfb8aa3b, v49
	v_exp_f32_e32 v47, v47
	s_waitcnt vmcnt(15)
	v_lshlrev_b32_e32 v63, 16, v202
	v_add_f32_e32 v47, 1.0, v47
	v_rcp_f32_e32 v58, v47
	v_rcp_f32_e32 v47, v42
	s_nop 0
	v_pk_mul_f32 v[46:47], v[46:47], v[62:63]
	s_nop 0
	v_add_f32_e32 v42, 0, v46
	v_add_f32_e32 v47, v42, v47
	v_mul_f32_e32 v42, 0xbfb8aa3b, v43
	v_exp_f32_e32 v42, v42
	v_and_b32_e32 v43, 0xffff0000, v202
	v_add_f32_e32 v42, 1.0, v42
	v_rcp_f32_e32 v55, v42
	v_and_b32_e32 v42, 0xffff0000, v200
	v_pk_mul_f32 v[42:43], v[54:55], v[42:43]
	s_nop 0
	v_add_f32_e32 v42, 0, v42
	v_add_f32_e32 v56, v42, v43
	v_mul_f32_e32 v42, 0xbfb8aa3b, v44
	v_exp_f32_e32 v42, v42
	v_lshlrev_b32_e32 v43, 16, v203
	v_add_co_u32_e32 v44, vcc, s44, v52
	v_add_f32_e32 v42, 1.0, v42
	v_rcp_f32_e32 v49, v42
	v_lshlrev_b32_e32 v42, 16, v201
	v_pk_mul_f32 v[42:43], v[48:49], v[42:43]
	s_nop 0
	v_add_f32_e32 v42, 0, v42
	v_add_f32_e32 v55, v42, v43
	v_mul_f32_e32 v42, 0xbfb8aa3b, v45
	v_exp_f32_e32 v42, v42
	v_and_b32_e32 v43, 0xffff0000, v203
	v_addc_co_u32_e32 v45, vcc, 0, v53, vcc
	v_add_f32_e32 v42, 1.0, v42
	v_rcp_f32_e32 v59, v42
	v_and_b32_e32 v42, 0xffff0000, v201
	v_rcp_f32_e32 v48, v38
	v_rcp_f32_e32 v49, v34
	v_pk_mul_f32 v[42:43], v[58:59], v[42:43]
	v_mul_f32_e32 v38, 0xbfb8aa3b, v39
	v_add_f32_e32 v42, 0, v42
	v_add_f32_e32 v54, v42, v43
	s_nop 0
	v_exp_f32_e32 v38, v38
	s_nop 0
	v_add_f32_e32 v38, 1.0, v38
	v_rcp_f32_e32 v46, v38
	v_mul_f32_e32 v38, 0xbfb8aa3b, v40
	v_exp_f32_e32 v38, v38
	s_waitcnt vmcnt(14)
	v_lshlrev_b32_e32 v52, 16, v204
	v_add_f32_e32 v38, 1.0, v38
	s_waitcnt vmcnt(13)
	v_lshlrev_b32_e32 v53, 16, v206
	v_pk_mul_f32 v[48:49], v[48:49], v[52:53]
	v_rcp_f32_e32 v40, v38
	v_add_f32_e32 v34, v47, v48
	v_add_f32_e32 v48, v34, v49
	v_mul_f32_e32 v34, 0xbfb8aa3b, v35
	v_exp_f32_e32 v34, v34
	v_and_b32_e32 v35, 0xffff0000, v206
	v_mul_f32_e32 v38, 0xbfb8aa3b, v41
	v_exp_f32_e32 v38, v38
	v_add_f32_e32 v34, 1.0, v34
	v_rcp_f32_e32 v47, v34
	v_and_b32_e32 v34, 0xffff0000, v204
	v_add_f32_e32 v38, 1.0, v38
	v_rcp_f32_e32 v38, v38
	v_pk_mul_f32 v[34:35], v[46:47], v[34:35]
	s_nop 0
	v_add_f32_e32 v34, v56, v34
	v_add_f32_e32 v42, v34, v35
	v_mul_f32_e32 v34, 0xbfb8aa3b, v36
	v_exp_f32_e32 v34, v34
	v_lshlrev_b32_e32 v35, 16, v207
	v_add_f32_e32 v34, 1.0, v34
	v_rcp_f32_e32 v41, v34
	v_lshlrev_b32_e32 v34, 16, v205
	v_pk_mul_f32 v[34:35], v[40:41], v[34:35]
	s_nop 0
	v_add_f32_e32 v34, v55, v34
	v_add_f32_e32 v36, v34, v35
	v_mul_f32_e32 v34, 0xbfb8aa3b, v37
	v_exp_f32_e32 v34, v34
	v_and_b32_e32 v35, 0xffff0000, v207
	v_add_f32_e32 v34, 1.0, v34
	v_rcp_f32_e32 v39, v34
	v_and_b32_e32 v34, 0xffff0000, v205
	v_pk_mul_f32 v[34:35], v[38:39], v[34:35]
	s_nop 0
	v_add_f32_e32 v34, v54, v34
	v_add_f32_e32 v35, v34, v35
	v_cvt_pk_bf16_f32 v34, v48, v42
	v_cvt_pk_bf16_f32 v35, v36, v35
	v_lshlrev_b64 v[36:37], 11, v[50:51]
	v_lshl_add_u64 v[36:37], s[8:9], 0, v[36:37]
	v_lshl_add_u64 v[36:37], v[36:37], 0, v[140:141]
	global_store_dwordx2 v[36:37], v[34:35], off
	v_add_u32_e32 v34, 0xa0, v142
	v_ashrrev_i32_e32 v35, 31, v34
	v_lshlrev_b64 v[36:37], 13, v[34:35]
	v_lshl_add_u64 v[36:37], s[6:7], 0, v[36:37]
	v_lshl_add_u64 v[36:37], v[36:37], 0, v[140:141]
	s_nop 0
	s_nop 0
	v_rcp_f32_e32 v38, v31
	v_mul_f32_e32 v31, 0xbfb8aa3b, v32
	v_exp_f32_e32 v31, v31
	s_waitcnt vmcnt(13)
	v_lshlrev_b32_e32 v46, 16, v208
	v_add_f32_e32 v31, 1.0, v31
	v_rcp_f32_e32 v32, v31
	v_mul_f32_e32 v31, 0xbfb8aa3b, v33
	v_exp_f32_e32 v31, v31
	s_waitcnt vmcnt(12)
	v_lshlrev_b32_e32 v47, 16, v228
	v_add_f32_e32 v31, 1.0, v31
	v_rcp_f32_e32 v42, v31
	v_rcp_f32_e32 v31, v26
	s_nop 0
	v_pk_mul_f32 v[30:31], v[30:31], v[46:47]
	s_nop 0
	v_add_f32_e32 v26, 0, v30
	v_add_f32_e32 v31, v26, v31
	v_mul_f32_e32 v26, 0xbfb8aa3b, v27
	v_exp_f32_e32 v26, v26
	v_and_b32_e32 v27, 0xffff0000, v228
	v_add_f32_e32 v26, 1.0, v26
	v_rcp_f32_e32 v39, v26
	v_and_b32_e32 v26, 0xffff0000, v208
	v_pk_mul_f32 v[26:27], v[38:39], v[26:27]
	s_nop 0
	v_add_f32_e32 v26, 0, v26
	v_add_f32_e32 v40, v26, v27
	v_mul_f32_e32 v26, 0xbfb8aa3b, v28
	v_exp_f32_e32 v26, v26
	v_lshlrev_b32_e32 v27, 16, v229
	v_add_co_u32_e32 v28, vcc, s44, v36
	v_add_f32_e32 v26, 1.0, v26
	v_rcp_f32_e32 v33, v26
	v_lshlrev_b32_e32 v26, 16, v209
	v_pk_mul_f32 v[26:27], v[32:33], v[26:27]
	s_nop 0
	v_add_f32_e32 v26, 0, v26
	v_add_f32_e32 v39, v26, v27
	v_mul_f32_e32 v26, 0xbfb8aa3b, v29
	v_exp_f32_e32 v26, v26
	v_and_b32_e32 v27, 0xffff0000, v229
	v_addc_co_u32_e32 v29, vcc, 0, v37, vcc
	v_add_f32_e32 v26, 1.0, v26
	v_rcp_f32_e32 v43, v26
	v_and_b32_e32 v26, 0xffff0000, v209
	v_rcp_f32_e32 v32, v22
	v_rcp_f32_e32 v33, v18
	v_pk_mul_f32 v[26:27], v[42:43], v[26:27]
	v_mul_f32_e32 v22, 0xbfb8aa3b, v23
	v_add_f32_e32 v26, 0, v26
	v_add_f32_e32 v38, v26, v27
	s_nop 0
	v_exp_f32_e32 v22, v22
	s_nop 0
	v_add_f32_e32 v22, 1.0, v22
	v_rcp_f32_e32 v30, v22
	v_mul_f32_e32 v22, 0xbfb8aa3b, v24
	v_exp_f32_e32 v22, v22
	s_waitcnt vmcnt(11)
	v_lshlrev_b32_e32 v36, 16, v230
	v_add_f32_e32 v22, 1.0, v22
	s_waitcnt vmcnt(10)
	v_lshlrev_b32_e32 v37, 16, v232
	v_pk_mul_f32 v[32:33], v[32:33], v[36:37]
	v_rcp_f32_e32 v24, v22
	v_add_f32_e32 v18, v31, v32
	v_add_f32_e32 v32, v18, v33
	v_mul_f32_e32 v18, 0xbfb8aa3b, v19
	v_exp_f32_e32 v18, v18
	v_and_b32_e32 v19, 0xffff0000, v232
	v_mul_f32_e32 v22, 0xbfb8aa3b, v25
	v_exp_f32_e32 v22, v22
	v_add_f32_e32 v18, 1.0, v18
	v_rcp_f32_e32 v31, v18
	v_and_b32_e32 v18, 0xffff0000, v230
	v_add_f32_e32 v22, 1.0, v22
	v_rcp_f32_e32 v22, v22
	v_pk_mul_f32 v[18:19], v[30:31], v[18:19]
	s_nop 0
	v_add_f32_e32 v18, v40, v18
	v_add_f32_e32 v26, v18, v19
	v_mul_f32_e32 v18, 0xbfb8aa3b, v20
	v_exp_f32_e32 v18, v18
	v_lshlrev_b32_e32 v19, 16, v233
	v_add_f32_e32 v18, 1.0, v18
	v_rcp_f32_e32 v25, v18
	v_lshlrev_b32_e32 v18, 16, v231
	v_pk_mul_f32 v[18:19], v[24:25], v[18:19]
	s_nop 0
	v_add_f32_e32 v18, v39, v18
	v_add_f32_e32 v20, v18, v19
	v_mul_f32_e32 v18, 0xbfb8aa3b, v21
	v_exp_f32_e32 v18, v18
	v_and_b32_e32 v19, 0xffff0000, v233
	v_add_f32_e32 v18, 1.0, v18
	v_rcp_f32_e32 v23, v18
	v_and_b32_e32 v18, 0xffff0000, v231
	v_pk_mul_f32 v[18:19], v[22:23], v[18:19]
	s_nop 0
	v_add_f32_e32 v18, v38, v18
	v_add_f32_e32 v19, v18, v19
	v_cvt_pk_bf16_f32 v18, v32, v26
	v_cvt_pk_bf16_f32 v19, v20, v19
	v_lshlrev_b64 v[20:21], 11, v[34:35]
	v_lshl_add_u64 v[20:21], s[8:9], 0, v[20:21]
	v_lshl_add_u64 v[20:21], v[20:21], 0, v[140:141]
	global_store_dwordx2 v[20:21], v[18:19], off
	v_add_u32_e32 v18, 0xb0, v142
	v_ashrrev_i32_e32 v19, 31, v18
	v_lshlrev_b64 v[20:21], 13, v[18:19]
	v_lshl_add_u64 v[20:21], s[6:7], 0, v[20:21]
	v_lshl_add_u64 v[20:21], v[20:21], 0, v[140:141]
	s_nop 0
	s_nop 0
	v_rcp_f32_e32 v22, v15
	v_mul_f32_e32 v15, 0xbfb8aa3b, v16
	v_exp_f32_e32 v15, v15
	s_waitcnt vmcnt(10)
	v_lshlrev_b32_e32 v30, 16, v234
	v_add_f32_e32 v15, 1.0, v15
	v_rcp_f32_e32 v16, v15
	v_mul_f32_e32 v15, 0xbfb8aa3b, v17
	v_exp_f32_e32 v15, v15
	s_waitcnt vmcnt(9)
	v_lshlrev_b32_e32 v31, 16, v236
	v_add_f32_e32 v15, 1.0, v15
	v_rcp_f32_e32 v26, v15
	v_rcp_f32_e32 v15, v10
	s_nop 0
	v_pk_mul_f32 v[14:15], v[14:15], v[30:31]
	s_nop 0
	v_add_f32_e32 v10, 0, v14
	v_add_f32_e32 v15, v10, v15
	v_mul_f32_e32 v10, 0xbfb8aa3b, v11
	v_exp_f32_e32 v10, v10
	v_and_b32_e32 v11, 0xffff0000, v236
	v_add_f32_e32 v10, 1.0, v10
	v_rcp_f32_e32 v23, v10
	v_and_b32_e32 v10, 0xffff0000, v234
	v_pk_mul_f32 v[10:11], v[22:23], v[10:11]
	s_nop 0
	v_add_f32_e32 v10, 0, v10
	v_add_f32_e32 v24, v10, v11
	v_mul_f32_e32 v10, 0xbfb8aa3b, v12
	v_exp_f32_e32 v10, v10
	v_lshlrev_b32_e32 v11, 16, v237
	v_add_co_u32_e32 v12, vcc, s44, v20
	v_add_f32_e32 v10, 1.0, v10
	v_rcp_f32_e32 v17, v10
	v_lshlrev_b32_e32 v10, 16, v235
	v_pk_mul_f32 v[10:11], v[16:17], v[10:11]
	s_nop 0
	v_add_f32_e32 v10, 0, v10
	v_add_f32_e32 v23, v10, v11
	v_mul_f32_e32 v10, 0xbfb8aa3b, v13
	v_exp_f32_e32 v10, v10
	v_and_b32_e32 v11, 0xffff0000, v237
	v_addc_co_u32_e32 v13, vcc, 0, v21, vcc
	v_add_f32_e32 v10, 1.0, v10
	v_rcp_f32_e32 v27, v10
	v_and_b32_e32 v10, 0xffff0000, v235
	v_rcp_f32_e32 v16, v6
	v_rcp_f32_e32 v17, v2
	v_pk_mul_f32 v[10:11], v[26:27], v[10:11]
	v_mul_f32_e32 v6, 0xbfb8aa3b, v7
	v_add_f32_e32 v10, 0, v10
	v_add_f32_e32 v22, v10, v11
	s_nop 0
	v_exp_f32_e32 v6, v6
	s_nop 0
	s_andn2_b64 vcc, exec, s[4:5]
	v_add_f32_e32 v6, 1.0, v6
	v_rcp_f32_e32 v14, v6
	v_mul_f32_e32 v6, 0xbfb8aa3b, v8
	v_exp_f32_e32 v6, v6
	s_waitcnt vmcnt(8)
	v_lshlrev_b32_e32 v20, 16, v238
	v_add_f32_e32 v6, 1.0, v6
	s_waitcnt vmcnt(7)
	v_lshlrev_b32_e32 v21, 16, v240
	v_pk_mul_f32 v[16:17], v[16:17], v[20:21]
	v_rcp_f32_e32 v8, v6
	v_add_f32_e32 v2, v15, v16
	v_add_f32_e32 v16, v2, v17
	v_mul_f32_e32 v2, 0xbfb8aa3b, v3
	v_exp_f32_e32 v2, v2
	v_and_b32_e32 v3, 0xffff0000, v240
	v_mul_f32_e32 v6, 0xbfb8aa3b, v9
	v_exp_f32_e32 v6, v6
	v_add_f32_e32 v2, 1.0, v2
	v_rcp_f32_e32 v15, v2
	v_and_b32_e32 v2, 0xffff0000, v238
	v_add_f32_e32 v6, 1.0, v6
	v_rcp_f32_e32 v6, v6
	v_pk_mul_f32 v[2:3], v[14:15], v[2:3]
	s_nop 0
	v_add_f32_e32 v2, v24, v2
	v_add_f32_e32 v10, v2, v3
	v_mul_f32_e32 v2, 0xbfb8aa3b, v4
	v_exp_f32_e32 v2, v2
	v_lshlrev_b32_e32 v3, 16, v241
	v_add_f32_e32 v2, 1.0, v2
	v_rcp_f32_e32 v9, v2
	v_lshlrev_b32_e32 v2, 16, v239
	v_pk_mul_f32 v[2:3], v[8:9], v[2:3]
	s_nop 0
	v_add_f32_e32 v2, v23, v2
	v_add_f32_e32 v4, v2, v3
	v_mul_f32_e32 v2, 0xbfb8aa3b, v5
	v_exp_f32_e32 v2, v2
	v_and_b32_e32 v3, 0xffff0000, v241
	v_add_f32_e32 v2, 1.0, v2
	v_rcp_f32_e32 v7, v2
	v_and_b32_e32 v2, 0xffff0000, v239
	v_pk_mul_f32 v[2:3], v[6:7], v[2:3]
	s_nop 0
	v_add_f32_e32 v2, v22, v2
	v_add_f32_e32 v3, v2, v3
	v_cvt_pk_bf16_f32 v2, v16, v10
	v_cvt_pk_bf16_f32 v3, v4, v3
	v_lshlrev_b64 v[4:5], 11, v[18:19]
	v_lshl_add_u64 v[4:5], s[8:9], 0, v[4:5]
	v_lshl_add_u64 v[4:5], v[4:5], 0, v[140:141]
	global_store_dwordx2 v[4:5], v[2:3], off
	s_cbranch_vccnz .LBB0_1599
	s_andn2_b64 vcc, exec, s[0:1]
	s_cbranch_vccnz .LBB0_1598
	s_barrier
	s_branch .LBB0_1598
